# code placement: GEMM K-loop heads and the NA attention loop head aligned to 64 bytes
# speedup vs baseline: 1.0011x; 1.0011x over previous
.LBB0_1006:
	s_mov_b32 s68, s65
	.p2align	6
